# M3 h*rstd stage: three rows of norm reads in flight with counted waits, immediate-offset addressing, unrelated copies after
# speedup vs baseline: 1.0082x; 1.0029x over previous
.LBB0_704:
	s_or_b64 exec, exec, s[0:1]
	v_lshl_add_u32 v71, v89, 7, s54
	s_waitcnt lgkmcnt(0)
	s_barrier
	v_lshlrev_b32_e32 v88, 2, v88
	v_and_b32_e32 v75, 0xffffffc0, v157
	v_add3_u32 v75, 0, v75, v88
	v_mad_u32_u24 v3, v89, s91, v75
	v_add_u32_e32 v46, 0x4200, v3
	ds_read_b128 v[88:91], v71
	ds_read_b128 v[92:95], v71 offset:16
	ds_read_b128 v[96:99], v71 offset:32
	ds_read_b128 v[100:103], v71 offset:48
	ds_read_b128 v[104:107], v71 offset:64
	ds_read_b128 v[108:111], v71 offset:80
	s_waitcnt lgkmcnt(4)
	v_pk_add_f32 v[90:91], v[90:91], v[94:95]
	v_pk_add_f32 v[88:89], v[88:89], v[92:93]
	v_add_f32_e32 v113, v90, v91
	v_add_f32_e32 v112, v89, v88
	ds_read_b128 v[88:91], v71 offset:96
	ds_read_b128 v[92:95], v71 offset:112
	v_add_f32_e32 v114, v112, v113
	v_fmamk_f32 v114, v114, 0x3c000000, v151
	v_rsq_f32_e32 v115, v114
	s_nop 0
	v_mul_f32_e32 v112, v56, v115
	ds_write_b32 v3, v112 offset:53248
	s_waitcnt lgkmcnt(5)
	v_pk_add_f32 v[98:99], v[98:99], v[102:103]
	v_pk_add_f32 v[96:97], v[96:97], v[100:101]
	v_add_f32_e32 v113, v98, v99
	v_add_f32_e32 v112, v97, v96
	ds_read_b128 v[96:99], v71 offset:512
	ds_read_b128 v[100:103], v71 offset:528
	v_add_f32_e32 v114, v112, v113
	v_fmamk_f32 v114, v114, 0x3c000000, v151
	v_rsq_f32_e32 v115, v114
	s_nop 0
	v_mul_f32_e32 v112, v59, v115
	ds_write_b32 v3, v112 offset:53776
	s_waitcnt lgkmcnt(6)
	v_pk_add_f32 v[106:107], v[106:107], v[110:111]
	v_pk_add_f32 v[104:105], v[104:105], v[108:109]
	v_add_f32_e32 v113, v106, v107
	v_add_f32_e32 v112, v105, v104
	ds_read_b128 v[104:107], v71 offset:544
	ds_read_b128 v[108:111], v71 offset:560
	v_add_f32_e32 v114, v112, v113
	v_fmamk_f32 v114, v114, 0x3c000000, v151
	v_rsq_f32_e32 v115, v114
	s_nop 0
	v_mul_f32_e32 v112, v58, v115
	ds_write_b32 v3, v112 offset:54304
	s_waitcnt lgkmcnt(7)
	v_pk_add_f32 v[90:91], v[90:91], v[94:95]
	v_pk_add_f32 v[88:89], v[88:89], v[92:93]
	v_add_f32_e32 v113, v90, v91
	v_add_f32_e32 v112, v89, v88
	ds_read_b128 v[88:91], v71 offset:576
	ds_read_b128 v[92:95], v71 offset:592
	v_add_f32_e32 v114, v112, v113
	v_fmamk_f32 v114, v114, 0x3c000000, v151
	v_rsq_f32_e32 v115, v114
	s_nop 0
	v_mul_f32_e32 v112, v83, v115
	ds_write_b32 v3, v112 offset:54832
	s_waitcnt lgkmcnt(7)
	v_pk_add_f32 v[98:99], v[98:99], v[102:103]
	v_pk_add_f32 v[96:97], v[96:97], v[100:101]
	v_add_f32_e32 v113, v98, v99
	v_add_f32_e32 v112, v97, v96
	ds_read_b128 v[96:99], v71 offset:608
	ds_read_b128 v[100:103], v71 offset:624
	v_add_f32_e32 v114, v112, v113
	v_fmamk_f32 v114, v114, 0x3c000000, v151
	v_rsq_f32_e32 v115, v114
	s_nop 0
	v_mul_f32_e32 v112, v52, v115
	ds_write_b32 v3, v112 offset:61696
	s_waitcnt lgkmcnt(7)
	v_pk_add_f32 v[106:107], v[106:107], v[110:111]
	v_pk_add_f32 v[104:105], v[104:105], v[108:109]
	v_add_f32_e32 v113, v106, v107
	v_add_f32_e32 v112, v105, v104
	ds_read_b128 v[104:107], v71 offset:1024
	ds_read_b128 v[108:111], v71 offset:1040
	v_add_f32_e32 v114, v112, v113
	v_fmamk_f32 v114, v114, 0x3c000000, v151
	v_rsq_f32_e32 v115, v114
	s_nop 0
	v_mul_f32_e32 v112, v77, v115
	ds_write_b32 v3, v112 offset:62224
	s_waitcnt lgkmcnt(7)
	v_pk_add_f32 v[90:91], v[90:91], v[94:95]
	v_pk_add_f32 v[88:89], v[88:89], v[92:93]
	v_add_f32_e32 v113, v90, v91
	v_add_f32_e32 v112, v89, v88
	ds_read_b128 v[88:91], v71 offset:1056
	ds_read_b128 v[92:95], v71 offset:1072
	v_add_f32_e32 v114, v112, v113
	v_fmamk_f32 v114, v114, 0x3c000000, v151
	v_rsq_f32_e32 v115, v114
	s_nop 0
	v_mul_f32_e32 v112, v53, v115
	ds_write_b32 v3, v112 offset:62752
	s_waitcnt lgkmcnt(7)
	v_pk_add_f32 v[98:99], v[98:99], v[102:103]
	v_pk_add_f32 v[96:97], v[96:97], v[100:101]
	v_add_f32_e32 v113, v98, v99
	v_add_f32_e32 v112, v97, v96
	ds_read_b128 v[96:99], v71 offset:1088
	ds_read_b128 v[100:103], v71 offset:1104
	v_add_f32_e32 v114, v112, v113
	v_fmamk_f32 v114, v114, 0x3c000000, v151
	v_rsq_f32_e32 v115, v114
	s_nop 0
	v_mul_f32_e32 v112, v54, v115
	ds_write_b32 v3, v112 offset:63280
	s_waitcnt lgkmcnt(7)
	v_pk_add_f32 v[106:107], v[106:107], v[110:111]
	v_pk_add_f32 v[104:105], v[104:105], v[108:109]
	v_add_f32_e32 v113, v106, v107
	v_add_f32_e32 v112, v105, v104
	ds_read_b128 v[104:107], v71 offset:1120
	ds_read_b128 v[108:111], v71 offset:1136
	v_add_f32_e32 v114, v112, v113
	v_fmamk_f32 v114, v114, 0x3c000000, v151
	v_rsq_f32_e32 v115, v114
	s_nop 0
	v_mul_f32_e32 v112, v48, v115
	ds_write_b32 v46, v112 offset:53248
	s_waitcnt lgkmcnt(7)
	v_pk_add_f32 v[90:91], v[90:91], v[94:95]
	v_pk_add_f32 v[88:89], v[88:89], v[92:93]
	v_add_f32_e32 v113, v90, v91
	v_add_f32_e32 v112, v89, v88
	ds_read_b128 v[88:91], v71 offset:1536
	ds_read_b128 v[92:95], v71 offset:1552
	v_add_f32_e32 v114, v112, v113
	v_fmamk_f32 v114, v114, 0x3c000000, v151
	v_rsq_f32_e32 v115, v114
	s_nop 0
	v_mul_f32_e32 v112, v73, v115
	ds_write_b32 v46, v112 offset:53776
	s_waitcnt lgkmcnt(7)
	v_pk_add_f32 v[98:99], v[98:99], v[102:103]
	v_pk_add_f32 v[96:97], v[96:97], v[100:101]
	v_add_f32_e32 v113, v98, v99
	v_add_f32_e32 v112, v97, v96
	ds_read_b128 v[96:99], v71 offset:1568
	ds_read_b128 v[100:103], v71 offset:1584
	v_add_f32_e32 v114, v112, v113
	v_fmamk_f32 v114, v114, 0x3c000000, v151
	v_rsq_f32_e32 v115, v114
	s_nop 0
	v_mul_f32_e32 v112, v49, v115
	ds_write_b32 v46, v112 offset:54304
	s_waitcnt lgkmcnt(7)
	v_pk_add_f32 v[106:107], v[106:107], v[110:111]
	v_pk_add_f32 v[104:105], v[104:105], v[108:109]
	v_add_f32_e32 v113, v106, v107
	v_add_f32_e32 v112, v105, v104
	ds_read_b128 v[104:107], v71 offset:1600
	ds_read_b128 v[108:111], v71 offset:1616
	v_add_f32_e32 v114, v112, v113
	v_fmamk_f32 v114, v114, 0x3c000000, v151
	v_rsq_f32_e32 v115, v114
	s_nop 0
	v_mul_f32_e32 v112, v50, v115
	ds_write_b32 v46, v112 offset:54832
	s_waitcnt lgkmcnt(7)
	v_pk_add_f32 v[90:91], v[90:91], v[94:95]
	v_pk_add_f32 v[88:89], v[88:89], v[92:93]
	v_add_f32_e32 v113, v90, v91
	v_add_f32_e32 v112, v89, v88
	ds_read_b128 v[88:91], v71 offset:1632
	ds_read_b128 v[92:95], v71 offset:1648
	v_add_f32_e32 v114, v112, v113
	v_fmamk_f32 v114, v114, 0x3c000000, v151
	v_rsq_f32_e32 v115, v114
	s_nop 0
	v_mul_f32_e32 v112, v51, v115
	ds_write_b32 v46, v112 offset:61696
	s_waitcnt lgkmcnt(7)
	v_pk_add_f32 v[98:99], v[98:99], v[102:103]
	v_pk_add_f32 v[96:97], v[96:97], v[100:101]
	v_add_f32_e32 v113, v98, v99
	v_add_f32_e32 v112, v97, v96
	v_add_f32_e32 v114, v112, v113
	v_fmamk_f32 v114, v114, 0x3c000000, v151
	v_rsq_f32_e32 v115, v114
	s_nop 0
	v_mul_f32_e32 v112, v68, v115
	ds_write_b32 v46, v112 offset:62224
	s_waitcnt lgkmcnt(5)
	v_pk_add_f32 v[106:107], v[106:107], v[110:111]
	v_pk_add_f32 v[104:105], v[104:105], v[108:109]
	v_add_f32_e32 v113, v106, v107
	v_add_f32_e32 v112, v105, v104
	v_add_f32_e32 v114, v112, v113
	v_fmamk_f32 v114, v114, 0x3c000000, v151
	v_rsq_f32_e32 v115, v114
	s_nop 0
	v_mul_f32_e32 v112, v45, v115
	ds_write_b32 v46, v112 offset:62752
	s_waitcnt lgkmcnt(3)
	v_pk_add_f32 v[90:91], v[90:91], v[94:95]
	v_pk_add_f32 v[88:89], v[88:89], v[92:93]
	v_add_f32_e32 v113, v90, v91
	v_add_f32_e32 v112, v89, v88
	v_add_f32_e32 v114, v112, v113
	v_fmamk_f32 v114, v114, 0x3c000000, v151
	v_rsq_f32_e32 v115, v114
	s_nop 0
	v_mul_f32_e32 v112, v44, v115
	ds_write_b32 v46, v112 offset:63280
	s_add_u32 s0, s36, s58
	v_readlane_b32 s56, v246, 4
	s_addc_u32 s1, s37, 0
	v_readlane_b32 s68, v246, 16
	v_readlane_b32 s69, v246, 17
	s_add_u32 s2, s68, s4
	s_addc_u32 s3, s69, 0
	s_waitcnt vmcnt(1)
	v_lshlrev_b32_e32 v75, 16, v67
	s_waitcnt vmcnt(0)
	v_and_b32_e32 v108, 0xffff0000, v60
	v_lshlrev_b32_e32 v109, 16, v61
	v_and_b32_e32 v113, 0xffff0000, v61
	v_lshlrev_b32_e32 v114, 16, v62
	v_and_b32_e32 v62, 0xffff0000, v62
	v_mov_b64_e32 v[106:107], v[22:23]
	v_mov_b64_e32 v[102:103], v[18:19]
	v_lshlrev_b32_e32 v115, 16, v63
	v_and_b32_e32 v63, 0xffff0000, v63
	v_lshl_add_u64 v[144:145], v[144:145], 0, s[16:17]
	v_mov_b32_e32 v112, v154
	v_mov_b32_e32 v111, v129
	v_mov_b64_e32 v[98:99], v[14:15]
	v_mov_b64_e32 v[104:105], v[20:21]
	v_mov_b64_e32 v[100:101], v[16:17]
	v_mov_b64_e32 v[96:97], v[12:13]
	v_mov_b32_e32 v110, v1
	s_add_i32 s38, s38, s39
	s_add_i32 s40, s40, s41
	v_mov_b32_e32 v158, v155
	v_readlane_b32 s57, v246, 5
	v_readlane_b32 s58, v246, 6
	v_readlane_b32 s59, v246, 7
	v_readlane_b32 s60, v246, 8
	v_readlane_b32 s61, v246, 9
	v_readlane_b32 s62, v246, 10
	v_readlane_b32 s63, v246, 11
	v_readlane_b32 s64, v246, 12
	v_readlane_b32 s65, v246, 13
	v_mov_b32_e32 v83, v0
	v_mov_b64_e32 v[94:95], v[10:11]
	v_mov_b64_e32 v[92:93], v[8:9]
	v_readlane_b32 s66, v246, 14
	v_readlane_b32 s67, v246, 15
	v_readlane_b32 s70, v246, 18
	v_readlane_b32 s71, v246, 19
	s_nop 0
	s_nop 0
	s_nop 0
	s_nop 1
	s_nop 0
	s_nop 0
	v_and_b32_e32 v76, 0xffff0000, v67
	s_nop 1
	s_nop 0
	v_mov_b64_e32 v[90:91], v[6:7]
	v_mov_b64_e32 v[88:89], v[4:5]
	s_nop 0
	s_nop 0
	s_nop 0
	s_nop 1
	s_nop 0
	s_nop 0
	v_lshlrev_b32_e32 v72, 16, v65
	v_and_b32_e32 v65, 0xffff0000, v65
	s_nop 0
	v_lshlrev_b32_e32 v73, 16, v66
	s_nop 0
	v_and_b32_e32 v74, 0xffff0000, v66
	v_lshl_add_u64 v[66:67], s[0:1], 0, v[82:83]
	s_nop 0
	s_nop 0
	s_nop 0
	s_nop 1
	v_lshlrev_b32_e32 v70, 2, v156
	v_and_b32_e32 v71, 0xffff0000, v64
	v_lshlrev_b64 v[58:59], 11, v[84:85]
	s_nop 1
	s_nop 0
	s_nop 0
	s_nop 0
	s_nop 1
	s_nop 0
	v_lshl_add_u64 v[68:69], v[66:67], 0, v[58:59]
	s_nop 0
	s_nop 1
	s_nop 0
	s_nop 0
	s_nop 0
	s_nop 1
	s_nop 0
	s_waitcnt lgkmcnt(0)
	s_barrier
	global_load_dwordx4 v[44:47], v70, s[2:3]
	global_load_dwordx4 v[48:51], v70, s[2:3] offset:16
	v_lshlrev_b32_e32 v3, 16, v64
	v_add_u32_e32 v64, 0, v70
	v_mad_u64_u32 v[56:57], s[12:13], v86, s95, v[64:65]
	ds_read_b128 v[52:55], v56 offset:53248
	ds_read_b128 v[56:59], v56 offset:53264
	v_mov_b64_e32 v[86:87], v[42:43]
	v_mov_b64_e32 v[84:85], v[40:41]
	s_andn2_b64 vcc, exec, s[24:25]
	s_waitcnt vmcnt(1) lgkmcnt(1)
	v_mul_f32_e32 v44, v52, v44
	v_mul_f32_e32 v45, v53, v45
	v_mul_f32_e32 v46, v54, v46
	v_mul_f32_e32 v47, v55, v47
	s_waitcnt vmcnt(0) lgkmcnt(0)
	v_mul_f32_e32 v48, v56, v48
	v_mul_f32_e32 v49, v57, v49
	v_mul_f32_e32 v50, v58, v50
	v_mul_f32_e32 v51, v59, v51
	v_mul_f32_e32 v3, v44, v3
	v_mul_f32_e32 v44, v45, v71
	v_mul_f32_e32 v45, v46, v72
	v_mul_f32_e32 v46, v47, v65
	v_mul_f32_e32 v47, v48, v73
	v_mul_f32_e32 v48, v49, v74
	v_mul_f32_e32 v49, v50, v75
	v_mul_f32_e32 v50, v51, v76
	v_cvt_pk_bf16_f32 v44, v3, v44
	v_cvt_pk_bf16_f32 v45, v45, v46
	v_cvt_pk_bf16_f32 v46, v47, v48
	v_cvt_pk_bf16_f32 v47, v49, v50
	global_store_dwordx4 v[68:69], v[44:47], off
	global_load_dwordx4 v[44:47], v70, s[2:3]
	s_nop 0
	global_load_dwordx4 v[48:51], v70, s[2:3] offset:16
	v_lshlrev_b32_e32 v65, 16, v60
	v_lshlrev_b64 v[52:53], 11, v[80:81]
	v_mad_u64_u32 v[2:3], s[0:1], v2, s95, v[64:65]
	v_lshl_add_u64 v[60:61], v[66:67], 0, v[52:53]
	ds_read_b128 v[52:55], v2 offset:53248
	ds_read_b128 v[56:59], v2 offset:53264
	v_mov_b64_e32 v[82:83], v[38:39]
	v_mov_b64_e32 v[74:75], v[34:35]
	v_mov_b64_e32 v[78:79], v[30:31]
	v_mov_b64_e32 v[70:71], v[26:27]
	v_mov_b64_e32 v[80:81], v[36:37]
	v_mov_b64_e32 v[72:73], v[32:33]
	v_mov_b64_e32 v[76:77], v[28:29]
	v_mov_b64_e32 v[68:69], v[24:25]
	s_waitcnt vmcnt(1) lgkmcnt(1)
	v_mul_f32_e32 v2, v52, v44
	v_mul_f32_e32 v3, v53, v45
	v_mul_f32_e32 v44, v54, v46
	v_mul_f32_e32 v45, v55, v47
	s_waitcnt vmcnt(0) lgkmcnt(0)
	v_mul_f32_e32 v46, v56, v48
	v_mul_f32_e32 v47, v57, v49
	v_mul_f32_e32 v48, v58, v50
	v_mul_f32_e32 v49, v59, v51
	v_mul_f32_e32 v45, v45, v113
	v_mul_f32_e32 v46, v46, v114
	v_mul_f32_e32 v47, v47, v62
	v_mul_f32_e32 v2, v2, v65
	v_mul_f32_e32 v3, v3, v108
	v_mul_f32_e32 v50, v44, v109
	v_mul_f32_e32 v48, v48, v115
	v_mul_f32_e32 v49, v49, v63
	v_cvt_pk_bf16_f32 v44, v2, v3
	v_cvt_pk_bf16_f32 v45, v50, v45
	v_cvt_pk_bf16_f32 v46, v46, v47
	v_cvt_pk_bf16_f32 v47, v48, v49
	global_store_dwordx4 v[60:61], v[44:47], off
	s_cbranch_vccz .LBB0_743
